# v51 + MLA loop: next-tile DMA block issued right behind each tile barrier (earlier by four QK MFMAs)
# speedup vs baseline: 1.0108x; 1.0080x over previous
.LBB0_543:
	s_mov_b32 s23, s17
	s_mov_b32 s17, s0
	s_add_u32 s4, s38, s20
	s_addc_u32 s5, s39, s21
	s_add_u32 s24, s4, 0x149ec400
	s_addc_u32 s25, s5, 0
	s_mov_b32 m0, s90
	v_lshl_add_u64 v[254:255], v[246:247], 0, s[24:25]
	s_lshl_b32 s18, s22, 14
	global_load_lds_dwordx4 v[254:255], off
	s_add_u32 s24, s4, 0x14a0c400
	s_addc_u32 s25, s5, 0
	s_mov_b32 m0, s91
	v_lshl_add_u64 v[254:255], v[246:247], 0, s[24:25]
	s_add_i32 s1, s89, s18
	global_load_lds_dwordx4 v[254:255], off
	s_add_u32 s24, s4, 0x149ec500
	s_addc_u32 s25, s5, 0
	s_mov_b32 m0, s1
	v_lshl_add_u64 v[254:255], v[248:249], 0, s[24:25]
	global_load_lds_dwordx4 v[254:255], off
	s_add_u32 s24, s4, 0x14a0c500
	s_addc_u32 s25, s5, 0
	s_add_i32 m0, s1, 0x2000
	v_lshl_add_u64 v[254:255], v[248:249], 0, s[24:25]
	global_load_lds_dwordx4 v[254:255], off
	s_add_u32 s4, s38, s88
	s_addc_u32 s5, s39, s87
	s_add_u32 s4, s4, s36
	s_addc_u32 s5, s5, s37
	s_mov_b32 m0, s92
	v_lshl_add_u64 v[254:255], v[250:251], 0, s[4:5]
	global_load_lds_dwordx4 v[254:255], off
	s_add_i32 s71, 0, 0x10000
	ds_read_b128 v[66:69], v174 offset:49152
	ds_read_b128 v[70:73], v174 offset:57344
	ds_read_b128 v[206:209], v176 offset:49152
	ds_read_b128 v[210:213], v176 offset:57344
	v_fma_f32 v152, v74, s34, v146
	v_fma_f32 v153, v75, s34, v146
	v_fma_f32 v150, v76, s34, v146
	v_fma_f32 v151, v77, s34, v146
	v_fma_f32 v148, v78, s34, v146
	v_fma_f32 v149, v79, s34, v146
	v_fma_f32 v147, v81, s34, v146
	v_fma_f32 v146, v80, s34, v146
	v_exp_f32_e32 v229, v229
	v_exp_f32_e32 v231, v231
	v_exp_f32_e32 v227, v227
	v_exp_f32_e32 v230, v230
	v_exp_f32_e32 v226, v226
	v_exp_f32_e32 v228, v228
	s_waitcnt lgkmcnt(0)
	v_mfma_f32_32x32x16_bf16 v[82:97], v[66:69], v[142:145], 0
	s_add_i32 s0, 0, 0x16000
	v_exp_f32_e32 v240, v146
	v_add_f32_e32 v146, 0, v229
	v_add_f32_e32 v146, v231, v146
	v_add_f32_e32 v146, v227, v146
	v_add_f32_e32 v146, v230, v146
	v_add_f32_e32 v146, v226, v146
	v_exp_f32_e32 v224, v224
	v_exp_f32_e32 v225, v225
	v_exp_f32_e32 v221, v221
	v_exp_f32_e32 v223, v223
	v_mfma_f32_32x32x16_bf16 v[66:81], v[70:73], v[142:145], 0
	v_exp_f32_e32 v220, v220
	v_exp_f32_e32 v222, v222
	v_add_f32_e32 v146, v228, v146
	v_add_f32_e32 v146, v224, v146
	v_add_f32_e32 v146, v225, v146
	v_add_f32_e32 v146, v221, v146
	v_add_f32_e32 v146, v223, v146
	v_add_f32_e32 v146, v220, v146
	v_add_f32_e32 v146, v222, v146
	v_exp_f32_e32 v217, v217
	v_exp_f32_e32 v219, v219
	v_exp_f32_e32 v216, v216
	v_exp_f32_e32 v218, v218
	v_mfma_f32_32x32x16_bf16 v[82:97], v[206:209], v[138:141], v[82:97]
	v_exp_f32_e32 v164, v164
	v_add_f32_e32 v146, v217, v146
	v_exp_f32_e32 v165, v165
	v_add_f32_e32 v146, v219, v146
	v_exp_f32_e32 v197, v162
	v_add_f32_e32 v146, v216, v146
	v_add_f32_e32 v146, v218, v146
	v_mfma_f32_32x32x16_bf16 v[66:81], v[210:213], v[138:141], v[66:81]
	ds_read_b128 v[206:209], v178 offset:49152
	ds_read_b128 v[210:213], v178 offset:57344
	v_exp_f32_e32 v156, v156
	v_add_f32_e32 v146, v164, v146
	v_exp_f32_e32 v157, v157
	v_add_f32_e32 v146, v165, v146
	v_add_f32_e32 v146, v197, v146
	v_exp_f32_e32 v241, v147
	s_waitcnt lgkmcnt(0)
	v_mfma_f32_32x32x16_bf16 v[82:97], v[206:209], v[134:137], v[82:97]
	v_mfma_f32_32x32x16_bf16 v[66:81], v[210:213], v[134:137], v[66:81]
	ds_read_b128 v[208:211], v180 offset:49152
	ds_read_b128 v[212:215], v180 offset:57344
	s_waitcnt lgkmcnt(0)
	v_mfma_f32_32x32x16_bf16 v[82:97], v[208:211], v[130:133], v[82:97]
	v_mfma_f32_32x32x16_bf16 v[66:81], v[212:215], v[130:133], v[66:81]
	ds_read_b128 v[208:211], v182 offset:49152
	ds_read_b128 v[212:215], v182 offset:57344
	s_waitcnt lgkmcnt(0)
	v_mfma_f32_32x32x16_bf16 v[82:97], v[208:211], v[126:129], v[82:97]
	v_mfma_f32_32x32x16_bf16 v[66:81], v[212:215], v[126:129], v[66:81]
	ds_read_b128 v[210:213], v186 offset:49152
	ds_read_b128 v[232:235], v186 offset:57344
	s_waitcnt lgkmcnt(0)
	v_mfma_f32_32x32x16_bf16 v[82:97], v[210:213], v[122:125], v[82:97]
	v_mfma_f32_32x32x16_bf16 v[66:81], v[232:235], v[122:125], v[66:81]
	ds_read_b128 v[210:213], v188 offset:49152
	ds_read_b128 v[232:235], v188 offset:57344
	s_waitcnt lgkmcnt(0)
	v_mfma_f32_32x32x16_bf16 v[82:97], v[210:213], v[118:121], v[82:97]
	v_mfma_f32_32x32x16_bf16 v[66:81], v[232:235], v[118:121], v[66:81]
	ds_read_b128 v[212:215], v190 offset:49152
	ds_read_b128 v[232:235], v190 offset:57344
	s_waitcnt lgkmcnt(0)
	v_mfma_f32_32x32x16_bf16 v[82:97], v[212:215], v[114:117], v[82:97]
	v_mfma_f32_32x32x16_bf16 v[66:81], v[232:235], v[114:117], v[66:81]
	ds_read_b128 v[212:215], v192 offset:8192
	ds_read_b128 v[232:235], v192 offset:12288
	s_waitcnt lgkmcnt(0)
	v_mfma_f32_32x32x16_bf16 v[82:97], v[212:215], v[110:113], v[82:97]
	v_exp_f32_e32 v215, v163
	s_nop 0
	v_add_f32_e32 v146, v215, v146
	v_mfma_f32_32x32x16_bf16 v[66:81], v[232:235], v[110:113], v[66:81]
	s_lshl_b32 s24, s17, 14
	v_add_u32_e32 v245, s24, v200
	ds_read_b64_tr_b16 v[206:207], v245 offset:0
	ds_read_b64_tr_b16 v[208:209], v245 offset:0x800
	ds_read_b64_tr_b16 v[210:211], v245 offset:0x1000
	ds_read_b64_tr_b16 v[212:213], v245 offset:0x1800
	ds_read_b128 v[232:235], v194 offset:8192
	ds_read_b128 v[236:239], v194 offset:12288
	v_add_f32_e32 v146, v156, v146
	v_add_f32_e32 v146, v157, v146
	s_waitcnt lgkmcnt(0)
	v_mfma_f32_32x32x16_bf16 v[82:97], v[232:235], v[106:109], v[82:97]
	v_mfma_f32_32x32x16_bf16 v[66:81], v[236:239], v[106:109], v[66:81]
	ds_read_b128 v[232:235], v196 offset:8192
	ds_read_b128 v[236:239], v196 offset:12288
	s_waitcnt lgkmcnt(0)
	v_mfma_f32_32x32x16_bf16 v[82:97], v[232:235], v[102:105], v[82:97]
	v_mfma_f32_32x32x16_bf16 v[66:81], v[236:239], v[102:105], v[66:81]
	ds_read_b128 v[232:235], v199 offset:8192
	ds_read_b128 v[236:239], v199 offset:12288
	s_waitcnt lgkmcnt(0)
	v_mfma_f32_32x32x16_bf16 v[82:97], v[232:235], v[98:101], v[82:97]
	v_exp_f32_e32 v232, v154
	v_exp_f32_e32 v233, v155
	v_exp_f32_e32 v234, v152
	v_exp_f32_e32 v235, v153
	v_add_f32_e32 v146, v232, v146
	v_add_f32_e32 v146, v233, v146
	v_add_f32_e32 v146, v234, v146
	v_mfma_f32_32x32x16_bf16 v[66:81], v[236:239], v[98:101], v[66:81]
	v_exp_f32_e32 v236, v150
	v_exp_f32_e32 v237, v151
	v_exp_f32_e32 v238, v148
	v_exp_f32_e32 v239, v149
	v_add_f32_e32 v146, v235, v146
	v_add_f32_e32 v146, v236, v146
	v_add_f32_e32 v146, v237, v146
	v_add_f32_e32 v146, v238, v146
	v_add_f32_e32 v146, v239, v146
	v_add_f32_e32 v146, v240, v146
	v_add_f32_e32 v162, v241, v146
	v_mov_b32_e32 v163, v162
	s_nop 1
	v_permlane32_swap_b32_e32 v162, v163
	v_cvt_pk_bf16_f32 v146, v229, v231
	v_cvt_pk_bf16_f32 v147, v227, v230
	v_cvt_pk_bf16_f32 v148, v226, v228
	v_cvt_pk_bf16_f32 v149, v224, v225
	v_cvt_pk_bf16_f32 v150, v221, v223
	v_cvt_pk_bf16_f32 v151, v220, v222
	v_cvt_pk_bf16_f32 v152, v217, v219
	v_cvt_pk_bf16_f32 v153, v216, v218
	v_cvt_pk_bf16_f32 v154, v164, v165
	v_cvt_pk_bf16_f32 v155, v197, v215
	v_cvt_pk_bf16_f32 v156, v156, v157
	v_cvt_pk_bf16_f32 v157, v232, v233
	v_cvt_pk_bf16_f32 v216, v234, v235
	v_cvt_pk_bf16_f32 v217, v236, v237
	v_cvt_pk_bf16_f32 v218, v238, v239
	v_cvt_pk_bf16_f32 v219, v240, v241
	s_nop 0
	v_permlane32_swap_b32_e32 v146, v148
	v_permlane32_swap_b32_e32 v147, v149
	v_permlane32_swap_b32_e32 v150, v152
	v_permlane32_swap_b32_e32 v151, v153
	v_permlane32_swap_b32_e32 v154, v156
	v_permlane32_swap_b32_e32 v155, v157
	v_permlane32_swap_b32_e32 v216, v218
	v_permlane32_swap_b32_e32 v217, v219
	s_lshl_b32 s24, s17, 14
	v_add_u32_e32 v197, s24, v200
	ds_read_b64_tr_b16 v[228:229], v197 offset:0x2000
	ds_read_b64_tr_b16 v[230:231], v197 offset:0x2800
	ds_read_b64_tr_b16 v[232:233], v197 offset:0x3000
	ds_read_b64_tr_b16 v[234:235], v197 offset:0x3800
	s_nop 0
	v_mfma_f32_32x32x16_bf16 v[2:17], v[146:149], v[206:209], v[2:17]
	ds_read_b64_tr_b16 v[220:221], v197 offset:0x200
	ds_read_b64_tr_b16 v[222:223], v197 offset:0xa00
	v_max_f32_e32 v164, v83, v83
	v_max_f32_e32 v165, v82, v82
	v_max_f32_e32 v164, v165, v164
	v_max3_f32 v164, v164, v84, v85
	v_max3_f32 v164, v164, v86, v87
	v_mfma_f32_32x32x16_bf16 v[2:17], v[150:153], v[210:213], v[2:17]
	ds_read_b64_tr_b16 v[224:225], v197 offset:0x1200
	ds_read_b64_tr_b16 v[226:227], v197 offset:0x1a00
	v_max3_f32 v164, v164, v88, v89
	v_max3_f32 v164, v164, v90, v91
	v_max3_f32 v164, v164, v92, v93
	v_max3_f32 v164, v164, v94, v95
	v_max3_f32 v164, v164, v96, v97
	s_waitcnt lgkmcnt(6)
	v_mfma_f32_32x32x16_bf16 v[2:17], v[154:157], v[228:231], v[2:17]
	ds_read_b64_tr_b16 v[228:229], v197 offset:0x2200
	ds_read_b64_tr_b16 v[230:231], v197 offset:0x2a00
	ds_read_b64_tr_b16 v[236:237], v197 offset:0x3200
	ds_read_b64_tr_b16 v[238:239], v197 offset:0x3a00
	s_waitcnt lgkmcnt(8)
	v_mfma_f32_32x32x16_bf16 v[2:17], v[216:219], v[232:235], v[2:17]
	s_waitcnt lgkmcnt(6)
	v_mfma_f32_32x32x16_bf16 v[50:65], v[146:149], v[220:223], v[50:65]
	v_max3_f32 v164, v164, v66, v67
	v_max3_f32 v164, v164, v68, v69
	v_max3_f32 v164, v164, v70, v71
	v_max3_f32 v164, v164, v72, v73
	v_max3_f32 v164, v164, v74, v75
	v_max3_f32 v164, v164, v76, v77
	v_max3_f32 v164, v164, v78, v79
	s_waitcnt lgkmcnt(4)
	v_mfma_f32_32x32x16_bf16 v[50:65], v[150:153], v[224:227], v[50:65]
	v_max3_f32 v164, v164, v80, v81
	v_mov_b32_e32 v165, v164
	s_nop 1
	v_permlane32_swap_b32_e32 v164, v165
	ds_read_b64_tr_b16 v[220:221], v197 offset:0x400
	v_max_f32_e32 v165, v165, v165
	v_max_f32_e32 v164, v164, v164
	s_waitcnt lgkmcnt(3)
	v_mfma_f32_32x32x16_bf16 v[50:65], v[154:157], v[228:231], v[50:65]
	ds_read_b64_tr_b16 v[222:223], v197 offset:0xc00
	v_max_f32_e32 v164, v164, v165
	v_max_f32_e32 v165, v202, v202
	ds_read_b64_tr_b16 v[224:225], v197 offset:0x1400
	v_max_f32_e32 v165, v165, v164
	ds_read_b64_tr_b16 v[226:227], v197 offset:0x1c00
	v_sub_f32_e32 v215, v164, v202
	s_waitcnt lgkmcnt(4)
	v_mfma_f32_32x32x16_bf16 v[50:65], v[216:219], v[236:239], v[50:65]
	v_sub_f32_e32 v164, v202, v165
	ds_read_b64_tr_b16 v[228:229], v197 offset:0x2400
	v_mul_f32_e32 v164, 0x3dd53b94, v164
	ds_read_b64_tr_b16 v[230:231], v197 offset:0x2c00
	v_exp_f32_e32 v164, v164
	ds_read_b64_tr_b16 v[232:233], v197 offset:0x3400
	v_cmp_ge_f32_e32 vcc, s77, v215
	ds_read_b64_tr_b16 v[234:235], v197 offset:0x3c00
	s_cmp_eq_u64 vcc, exec
	s_cselect_b64 s[4:5], -1, 0
	v_cndmask_b32_e64 v164, v164, 1.0, s[4:5]
	s_waitcnt lgkmcnt(6)
	v_mfma_f32_32x32x16_bf16 v[34:49], v[146:149], v[220:223], v[34:49]
	ds_read_b64_tr_b16 v[220:221], v197 offset:0x600
	ds_read_b64_tr_b16 v[222:223], v197 offset:0xe00
	s_waitcnt lgkmcnt(6)
	v_mfma_f32_32x32x16_bf16 v[34:49], v[150:153], v[224:227], v[34:49]
	ds_read_b64_tr_b16 v[224:225], v197 offset:0x1600
	ds_read_b64_tr_b16 v[226:227], v197 offset:0x1e00
	s_waitcnt lgkmcnt(6)
	v_mfma_f32_32x32x16_bf16 v[34:49], v[154:157], v[228:231], v[34:49]
	ds_read_b64_tr_b16 v[228:229], v197 offset:0x2600
	ds_read_b64_tr_b16 v[230:231], v197 offset:0x2e00
	ds_read_b64_tr_b16 v[236:237], v197 offset:0x3600
	ds_read_b64_tr_b16 v[238:239], v197 offset:0x3e00
	s_waitcnt lgkmcnt(8)
	v_mfma_f32_32x32x16_bf16 v[34:49], v[216:219], v[232:235], v[34:49]
	s_waitcnt lgkmcnt(6)
	v_mfma_f32_32x32x16_bf16 v[18:33], v[146:149], v[220:223], v[18:33]
	v_cmp_gt_f32_e32 vcc, 1.0, v164
	s_waitcnt lgkmcnt(4)
	v_mfma_f32_32x32x16_bf16 v[18:33], v[150:153], v[224:227], v[18:33]
	s_waitcnt lgkmcnt(2)
	v_mfma_f32_32x32x16_bf16 v[18:33], v[154:157], v[228:231], v[18:33]
	s_waitcnt lgkmcnt(0)
	v_mfma_f32_32x32x16_bf16 v[18:33], v[216:219], v[236:239], v[18:33]
	s_cbranch_vccz .LBB0_547
	s_and_saveexec_b64 s[0:1], s[2:3]
	ds_write_b32 v170, v164 offset:128
	s_or_b64 exec, exec, s[0:1]
	s_waitcnt lgkmcnt(0)
	ds_read_b128 v[146:149], v158 offset:224
	ds_read_b128 v[150:153], v158 offset:192
	ds_read_b128 v[154:157], v158 offset:160
	ds_read_b128 v[216:219], v158 offset:128
	s_waitcnt lgkmcnt(0)
	v_pk_mul_f32 v[16:17], v[16:17], v[148:149]
	v_pk_mul_f32 v[12:13], v[12:13], v[152:153]
	v_pk_mul_f32 v[8:9], v[8:9], v[156:157]
	v_pk_mul_f32 v[4:5], v[4:5], v[218:219]
	v_pk_mul_f32 v[14:15], v[14:15], v[146:147]
	v_pk_mul_f32 v[10:11], v[10:11], v[150:151]
	v_pk_mul_f32 v[6:7], v[6:7], v[154:155]
	v_pk_mul_f32 v[2:3], v[2:3], v[216:217]
	v_pk_mul_f32 v[64:65], v[64:65], v[148:149]
	v_pk_mul_f32 v[60:61], v[60:61], v[152:153]
	v_pk_mul_f32 v[56:57], v[56:57], v[156:157]
	v_pk_mul_f32 v[52:53], v[52:53], v[218:219]
	v_pk_mul_f32 v[62:63], v[62:63], v[146:147]
	v_pk_mul_f32 v[58:59], v[58:59], v[150:151]
	v_pk_mul_f32 v[54:55], v[54:55], v[154:155]
	v_pk_mul_f32 v[50:51], v[50:51], v[216:217]
	v_pk_mul_f32 v[48:49], v[48:49], v[148:149]
	v_pk_mul_f32 v[44:45], v[44:45], v[152:153]
	v_pk_mul_f32 v[40:41], v[40:41], v[156:157]
	v_pk_mul_f32 v[36:37], v[36:37], v[218:219]
	v_pk_mul_f32 v[46:47], v[46:47], v[146:147]
	v_pk_mul_f32 v[42:43], v[42:43], v[150:151]
	v_pk_mul_f32 v[38:39], v[38:39], v[154:155]
	v_pk_mul_f32 v[34:35], v[34:35], v[216:217]
	v_pk_mul_f32 v[32:33], v[32:33], v[148:149]
	v_pk_mul_f32 v[28:29], v[28:29], v[152:153]
	v_pk_mul_f32 v[24:25], v[24:25], v[156:157]
	v_pk_mul_f32 v[20:21], v[20:21], v[218:219]
	v_pk_mul_f32 v[30:31], v[30:31], v[146:147]
	v_pk_mul_f32 v[26:27], v[26:27], v[150:151]
	v_pk_mul_f32 v[22:23], v[22:23], v[154:155]
	v_pk_mul_f32 v[18:19], v[18:19], v[216:217]

.LBB0_549:
	s_cmp_lg_u32 s98, 0
	s_cbranch_scc1 .Lattn_mla_nopf
	s_add_u32 s0, s38, s20
	s_addc_u32 s1, s39, s21
	s_add_u32 s100, s0, s42
	s_addc_u32 s101, s1, s43
	s_mov_b32 m0, s93
	v_lshl_add_u64 v[254:255], v[246:247], 0, s[100:101]
	global_load_lds_dwordx4 v[254:255], off
	s_add_u32 s100, s0, s46
	s_addc_u32 s101, s1, s47
	s_mov_b32 m0, s94
	v_lshl_add_u64 v[254:255], v[246:247], 0, s[100:101]
	global_load_lds_dwordx4 v[254:255], off
	s_add_u32 s100, s0, s44
	s_addc_u32 s101, s1, s45
	s_add_i32 s98, s89, s24
	s_mov_b32 m0, s98
	v_lshl_add_u64 v[254:255], v[248:249], 0, s[100:101]
	global_load_lds_dwordx4 v[254:255], off
	s_add_u32 s100, s0, s50
	s_addc_u32 s101, s1, s51
	s_add_i32 m0, s98, 0x2000
	v_lshl_add_u64 v[254:255], v[248:249], 0, s[100:101]
	global_load_lds_dwordx4 v[254:255], off
	s_add_u32 s0, s38, s88
	s_addc_u32 s1, s39, s87
	s_add_u32 s0, s0, s58
	s_addc_u32 s1, s1, s59
	s_mov_b32 m0, s95
	v_lshl_add_u64 v[254:255], v[250:251], 0, s[0:1]
	global_load_lds_dwordx4 v[254:255], off
.Lattn_mla_nopf:
	v_cndmask_b32_e64 v165, v165, v202, s[4:5]
	v_mul_f32_e32 v154, 0xbdd53b94, v165
	v_fmamk_f32 v202, v69, 0x3dd53b94, v154
	v_fmamk_f32 v215, v70, 0x3dd53b94, v154
	v_fmamk_f32 v155, v66, 0x3dd53b94, v154
	v_fmamk_f32 v156, v67, 0x3dd53b94, v154
	v_fmamk_f32 v157, v68, 0x3dd53b94, v154
	v_fmamk_f32 v216, v71, 0x3dd53b94, v154
	v_fmamk_f32 v217, v72, 0x3dd53b94, v154
	v_fmamk_f32 v218, v73, 0x3dd53b94, v154
	ds_read_b128 v[66:69], v174 offset:32768
	ds_read_b128 v[70:73], v174 offset:40960
	ds_read_b128 v[146:149], v176 offset:32768
	ds_read_b128 v[150:153], v176 offset:40960
	v_fmamk_f32 v224, v82, 0x3dd53b94, v154
	v_fmamk_f32 v225, v83, 0x3dd53b94, v154
	v_fmamk_f32 v226, v84, 0x3dd53b94, v154
	v_fmamk_f32 v227, v85, 0x3dd53b94, v154
	v_fmamk_f32 v228, v86, 0x3dd53b94, v154
	v_fmamk_f32 v229, v87, 0x3dd53b94, v154
	v_fmamk_f32 v230, v88, 0x3dd53b94, v154
	v_fmamk_f32 v231, v89, 0x3dd53b94, v154
	v_fmamk_f32 v234, v90, 0x3dd53b94, v154
	v_fmamk_f32 v235, v91, 0x3dd53b94, v154
	v_fmamk_f32 v236, v92, 0x3dd53b94, v154
	v_fmamk_f32 v237, v93, 0x3dd53b94, v154
	v_fmamk_f32 v238, v94, 0x3dd53b94, v154
	v_fmamk_f32 v239, v95, 0x3dd53b94, v154
	v_fmamk_f32 v240, v96, 0x3dd53b94, v154
	v_fmamk_f32 v241, v97, 0x3dd53b94, v154
	s_waitcnt lgkmcnt(0)
	v_mfma_f32_32x32x16_bf16 v[82:97], v[66:69], v[142:145], 0
	v_fmamk_f32 v232, v79, 0x3dd53b94, v154
	v_fmamk_f32 v233, v80, 0x3dd53b94, v154
	v_fmamk_f32 v219, v74, 0x3dd53b94, v154
	v_fmamk_f32 v220, v75, 0x3dd53b94, v154
	v_fmamk_f32 v221, v76, 0x3dd53b94, v154
	v_fmamk_f32 v222, v77, 0x3dd53b94, v154
	v_fmamk_f32 v223, v78, 0x3dd53b94, v154
	v_fmac_f32_e32 v154, 0x3dd53b94, v81
	v_mfma_f32_32x32x16_bf16 v[66:81], v[70:73], v[142:145], 0
	v_exp_f32_e32 v224, v224
	v_exp_f32_e32 v225, v225
	v_exp_f32_e32 v226, v226
	v_add_f32_e32 v245, 0, v224
	v_add_f32_e32 v245, v225, v245
	v_add_f32_e32 v245, v226, v245
	v_mfma_f32_32x32x16_bf16 v[82:97], v[146:149], v[138:141], v[82:97]
	v_exp_f32_e32 v227, v227
	v_exp_f32_e32 v228, v228
	v_add_f32_e32 v245, v227, v245
	v_add_f32_e32 v245, v228, v245
	v_mfma_f32_32x32x16_bf16 v[66:81], v[150:153], v[138:141], v[66:81]
	ds_read_b128 v[146:149], v178 offset:32768
	ds_read_b128 v[150:153], v178 offset:40960
	v_exp_f32_e32 v229, v229
	v_exp_f32_e32 v230, v230
	v_add_f32_e32 v245, v229, v245
	v_add_f32_e32 v245, v230, v245
	s_waitcnt lgkmcnt(0)
	v_mfma_f32_32x32x16_bf16 v[82:97], v[146:149], v[134:137], v[82:97]
	v_mfma_f32_32x32x16_bf16 v[66:81], v[150:153], v[134:137], v[66:81]
	ds_read_b128 v[146:149], v180 offset:32768
	ds_read_b128 v[150:153], v180 offset:40960
	v_exp_f32_e32 v231, v231
	v_exp_f32_e32 v234, v234
	v_exp_f32_e32 v235, v235
	v_add_f32_e32 v245, v231, v245
	v_add_f32_e32 v245, v234, v245
	v_add_f32_e32 v245, v235, v245
	s_waitcnt lgkmcnt(0)
	v_mfma_f32_32x32x16_bf16 v[82:97], v[146:149], v[130:133], v[82:97]
	v_mfma_f32_32x32x16_bf16 v[66:81], v[150:153], v[130:133], v[66:81]
	ds_read_b128 v[146:149], v182 offset:32768
	ds_read_b128 v[150:153], v182 offset:40960
	v_exp_f32_e32 v236, v236
	v_exp_f32_e32 v237, v237
	v_exp_f32_e32 v238, v238
	v_add_f32_e32 v245, v236, v245
	v_add_f32_e32 v245, v237, v245
	v_add_f32_e32 v245, v238, v245
	s_waitcnt lgkmcnt(0)
	v_mfma_f32_32x32x16_bf16 v[82:97], v[146:149], v[126:129], v[82:97]
	v_mfma_f32_32x32x16_bf16 v[66:81], v[150:153], v[126:129], v[66:81]
	ds_read_b128 v[146:149], v186 offset:32768
	ds_read_b128 v[150:153], v186 offset:40960
	v_exp_f32_e32 v239, v239
	v_exp_f32_e32 v240, v240
	v_exp_f32_e32 v241, v241
	v_add_f32_e32 v245, v239, v245
	v_add_f32_e32 v245, v240, v245
	v_add_f32_e32 v245, v241, v245
	s_waitcnt lgkmcnt(0)
	v_mfma_f32_32x32x16_bf16 v[82:97], v[146:149], v[122:125], v[82:97]
	v_mfma_f32_32x32x16_bf16 v[66:81], v[150:153], v[122:125], v[66:81]
	ds_read_b128 v[146:149], v188 offset:32768
	ds_read_b128 v[150:153], v188 offset:40960
	v_exp_f32_e32 v155, v155
	v_exp_f32_e32 v156, v156
	v_exp_f32_e32 v157, v157
	v_add_f32_e32 v245, v155, v245
	v_add_f32_e32 v245, v156, v245
	v_add_f32_e32 v245, v157, v245
	s_waitcnt lgkmcnt(0)
	v_mfma_f32_32x32x16_bf16 v[82:97], v[146:149], v[118:121], v[82:97]
	v_mfma_f32_32x32x16_bf16 v[66:81], v[150:153], v[118:121], v[66:81]
	ds_read_b128 v[146:149], v190 offset:32768
	ds_read_b128 v[150:153], v190 offset:40960
	v_exp_f32_e32 v202, v202
	v_exp_f32_e32 v215, v215
	v_exp_f32_e32 v216, v216
	v_add_f32_e32 v245, v202, v245
	v_add_f32_e32 v245, v215, v245
	v_add_f32_e32 v245, v216, v245
	s_waitcnt lgkmcnt(0)
	v_mfma_f32_32x32x16_bf16 v[82:97], v[146:149], v[114:117], v[82:97]
	v_mfma_f32_32x32x16_bf16 v[66:81], v[150:153], v[114:117], v[66:81]
	ds_read_b128 v[146:149], v192
	ds_read_b128 v[150:153], v192 offset:4096
	v_exp_f32_e32 v217, v217
	v_exp_f32_e32 v218, v218
	v_exp_f32_e32 v219, v219
	v_add_f32_e32 v245, v217, v245
	v_add_f32_e32 v245, v218, v245
	v_add_f32_e32 v245, v219, v245
	s_waitcnt lgkmcnt(0)
	v_mfma_f32_32x32x16_bf16 v[82:97], v[146:149], v[110:113], v[82:97]
	v_mfma_f32_32x32x16_bf16 v[66:81], v[150:153], v[110:113], v[66:81]
	ds_read_b128 v[146:149], v194
	ds_read_b128 v[150:153], v194 offset:4096
	v_exp_f32_e32 v220, v220
	v_exp_f32_e32 v221, v221
	v_exp_f32_e32 v222, v222
	v_add_f32_e32 v245, v220, v245
	v_add_f32_e32 v245, v221, v245
	v_add_f32_e32 v245, v222, v245
	s_waitcnt lgkmcnt(0)
	v_mfma_f32_32x32x16_bf16 v[82:97], v[146:149], v[106:109], v[82:97]
	v_mfma_f32_32x32x16_bf16 v[66:81], v[150:153], v[106:109], v[66:81]
	ds_read_b128 v[146:149], v196
	ds_read_b128 v[150:153], v196 offset:4096
	v_exp_f32_e32 v223, v223
	v_exp_f32_e32 v242, v232
	v_exp_f32_e32 v243, v233
	v_add_f32_e32 v245, v223, v245
	v_add_f32_e32 v245, v242, v245
	v_add_f32_e32 v245, v243, v245
	s_waitcnt lgkmcnt(0)
	v_mfma_f32_32x32x16_bf16 v[82:97], v[146:149], v[102:105], v[82:97]
	v_mfma_f32_32x32x16_bf16 v[66:81], v[150:153], v[102:105], v[66:81]
	ds_read_b128 v[146:149], v199
	ds_read_b128 v[150:153], v199 offset:4096
	v_lshl_add_u32 v214, s23, 14, v200
	ds_read_b64_tr_b16 v[206:207], v214 offset:0
	ds_read_b64_tr_b16 v[208:209], v214 offset:0x800
	ds_read_b64_tr_b16 v[210:211], v214 offset:0x1000
	ds_read_b64_tr_b16 v[212:213], v214 offset:0x1800
	v_exp_f32_e32 v244, v154
	s_waitcnt lgkmcnt(4)
	v_mfma_f32_32x32x16_bf16 v[82:97], v[146:149], v[98:101], v[82:97]
	v_mfma_f32_32x32x16_bf16 v[66:81], v[150:153], v[98:101], v[66:81]
	v_add_f32_e32 v232, v244, v245
	v_mov_b32_e32 v233, v232
	s_nop 1
	v_permlane32_swap_b32_e32 v232, v233
	v_cvt_pk_bf16_f32 v146, v224, v225
	v_cvt_pk_bf16_f32 v147, v226, v227
	v_cvt_pk_bf16_f32 v148, v228, v229
	v_cvt_pk_bf16_f32 v149, v230, v231
	v_cvt_pk_bf16_f32 v150, v234, v235
	v_cvt_pk_bf16_f32 v151, v236, v237
	v_cvt_pk_bf16_f32 v152, v238, v239
	v_cvt_pk_bf16_f32 v153, v240, v241
	v_cvt_pk_bf16_f32 v154, v155, v156
	v_cvt_pk_bf16_f32 v155, v157, v202
	v_cvt_pk_bf16_f32 v156, v215, v216
	v_cvt_pk_bf16_f32 v157, v217, v218
	v_cvt_pk_bf16_f32 v216, v219, v220
	v_cvt_pk_bf16_f32 v217, v221, v222
	v_cvt_pk_bf16_f32 v218, v223, v242
	v_cvt_pk_bf16_f32 v219, v243, v244
	s_nop 0
	v_permlane32_swap_b32_e32 v146, v148
	v_permlane32_swap_b32_e32 v147, v149
	v_permlane32_swap_b32_e32 v150, v152
	v_permlane32_swap_b32_e32 v151, v153
	v_permlane32_swap_b32_e32 v154, v156
	v_permlane32_swap_b32_e32 v155, v157
	v_permlane32_swap_b32_e32 v216, v218
	v_permlane32_swap_b32_e32 v217, v219
	ds_read_b64_tr_b16 v[228:229], v214 offset:0x2000
	ds_read_b64_tr_b16 v[230:231], v214 offset:0x2800
	ds_read_b64_tr_b16 v[234:235], v214 offset:0x3000
	ds_read_b64_tr_b16 v[236:237], v214 offset:0x3800
	s_nop 0
	s_waitcnt lgkmcnt(6)
	v_mfma_f32_32x32x16_bf16 v[2:17], v[146:149], v[206:209], v[2:17]
	ds_read_b64_tr_b16 v[220:221], v214 offset:0x200
	ds_read_b64_tr_b16 v[222:223], v214 offset:0xa00
	v_max_f32_e32 v202, v83, v83
	v_max_f32_e32 v215, v82, v82
	v_max_f32_e32 v202, v215, v202
	v_max3_f32 v202, v202, v84, v85
	v_max3_f32 v202, v202, v86, v87
	s_waitcnt lgkmcnt(6)
	v_mfma_f32_32x32x16_bf16 v[2:17], v[150:153], v[210:213], v[2:17]
	ds_read_b64_tr_b16 v[224:225], v214 offset:0x1200
	ds_read_b64_tr_b16 v[226:227], v214 offset:0x1a00
	v_max3_f32 v202, v202, v88, v89
	v_max3_f32 v202, v202, v90, v91
	v_max3_f32 v202, v202, v92, v93
	v_max3_f32 v202, v202, v94, v95
	v_max3_f32 v202, v202, v96, v97
	s_waitcnt lgkmcnt(6)
	v_mfma_f32_32x32x16_bf16 v[2:17], v[154:157], v[228:231], v[2:17]
	ds_read_b64_tr_b16 v[228:229], v214 offset:0x2200
	ds_read_b64_tr_b16 v[230:231], v214 offset:0x2a00
	ds_read_b64_tr_b16 v[238:239], v214 offset:0x3200
	ds_read_b64_tr_b16 v[240:241], v214 offset:0x3a00
	s_waitcnt lgkmcnt(8)
	v_mfma_f32_32x32x16_bf16 v[2:17], v[216:219], v[234:237], v[2:17]
	s_waitcnt lgkmcnt(6)
	v_mfma_f32_32x32x16_bf16 v[50:65], v[146:149], v[220:223], v[50:65]
	v_max3_f32 v202, v202, v66, v67
	v_max3_f32 v202, v202, v68, v69
	v_max3_f32 v202, v202, v70, v71
	v_max3_f32 v202, v202, v72, v73
	v_max3_f32 v202, v202, v74, v75
	v_max3_f32 v202, v202, v76, v77
	v_max3_f32 v202, v202, v78, v79
	s_waitcnt lgkmcnt(4)
	v_mfma_f32_32x32x16_bf16 v[50:65], v[150:153], v[224:227], v[50:65]
	v_max3_f32 v202, v202, v80, v81
	v_mov_b32_e32 v215, v202
	s_nop 1
	v_permlane32_swap_b32_e32 v202, v215
	v_max_f32_e32 v215, v215, v215
	v_max_f32_e32 v202, v202, v202
	v_max_f32_e32 v202, v202, v215
	v_max_f32_e32 v220, v165, v165
	v_sub_f32_e32 v215, v202, v165
	v_max_f32_e32 v202, v220, v202
	v_sub_f32_e32 v220, v165, v202
	v_mul_f32_e32 v220, 0x3dd53b94, v220
	s_waitcnt lgkmcnt(2)
	v_mfma_f32_32x32x16_bf16 v[50:65], v[154:157], v[228:231], v[50:65]
	v_exp_f32_e32 v220, v220
	v_cmp_ge_f32_e32 vcc, s77, v215
	s_cmp_eq_u64 vcc, exec
	s_cselect_b64 s[4:5], -1, 0
	v_cndmask_b32_e64 v215, v220, 1.0, s[4:5]
	ds_read_b64_tr_b16 v[220:221], v214 offset:0x400
	ds_read_b64_tr_b16 v[222:223], v214 offset:0xc00
	ds_read_b64_tr_b16 v[224:225], v214 offset:0x1400
	s_waitcnt lgkmcnt(3)
	v_mfma_f32_32x32x16_bf16 v[50:65], v[216:219], v[238:241], v[50:65]
	ds_read_b64_tr_b16 v[226:227], v214 offset:0x1c00
	ds_read_b64_tr_b16 v[228:229], v214 offset:0x2400
	ds_read_b64_tr_b16 v[230:231], v214 offset:0x2c00
	ds_read_b64_tr_b16 v[234:235], v214 offset:0x3400
	ds_read_b64_tr_b16 v[236:237], v214 offset:0x3c00
	s_waitcnt lgkmcnt(6)
	v_mfma_f32_32x32x16_bf16 v[34:49], v[146:149], v[220:223], v[34:49]
	ds_read_b64_tr_b16 v[220:221], v214 offset:0x600
	ds_read_b64_tr_b16 v[222:223], v214 offset:0xe00
	s_waitcnt lgkmcnt(6)
	v_mfma_f32_32x32x16_bf16 v[34:49], v[150:153], v[224:227], v[34:49]
	ds_read_b64_tr_b16 v[224:225], v214 offset:0x1600
	ds_read_b64_tr_b16 v[226:227], v214 offset:0x1e00
	s_waitcnt lgkmcnt(6)
	v_mfma_f32_32x32x16_bf16 v[34:49], v[154:157], v[228:231], v[34:49]
	ds_read_b64_tr_b16 v[228:229], v214 offset:0x2600
	ds_read_b64_tr_b16 v[230:231], v214 offset:0x2e00
	ds_read_b64_tr_b16 v[238:239], v214 offset:0x3600
	ds_read_b64_tr_b16 v[240:241], v214 offset:0x3e00
	s_waitcnt lgkmcnt(8)
	v_mfma_f32_32x32x16_bf16 v[34:49], v[216:219], v[234:237], v[34:49]
	s_waitcnt lgkmcnt(6)
	v_mfma_f32_32x32x16_bf16 v[18:33], v[146:149], v[220:223], v[18:33]
	v_cmp_gt_f32_e32 vcc, 1.0, v215
	s_waitcnt lgkmcnt(4)
	v_mfma_f32_32x32x16_bf16 v[18:33], v[150:153], v[224:227], v[18:33]
	s_waitcnt lgkmcnt(2)
	v_mfma_f32_32x32x16_bf16 v[18:33], v[154:157], v[228:231], v[18:33]
	s_waitcnt lgkmcnt(0)
	v_mfma_f32_32x32x16_bf16 v[18:33], v[216:219], v[238:241], v[18:33]
	s_cbranch_vccz .LBB0_553
	s_and_saveexec_b64 s[0:1], s[2:3]
	ds_write_b32 v170, v215 offset:128
	s_or_b64 exec, exec, s[0:1]
	s_waitcnt lgkmcnt(0)
	ds_read_b128 v[146:149], v158 offset:224
	ds_read_b128 v[150:153], v158 offset:192
	ds_read_b128 v[154:157], v158 offset:160
	ds_read_b128 v[216:219], v158 offset:128
	s_waitcnt lgkmcnt(0)
	v_pk_mul_f32 v[16:17], v[16:17], v[148:149]
	v_pk_mul_f32 v[12:13], v[12:13], v[152:153]
	v_pk_mul_f32 v[8:9], v[8:9], v[156:157]
	v_pk_mul_f32 v[4:5], v[4:5], v[218:219]
	v_pk_mul_f32 v[14:15], v[14:15], v[146:147]
	v_pk_mul_f32 v[10:11], v[10:11], v[150:151]
	v_pk_mul_f32 v[6:7], v[6:7], v[154:155]
	v_pk_mul_f32 v[2:3], v[2:3], v[216:217]
	v_pk_mul_f32 v[64:65], v[64:65], v[148:149]
	v_pk_mul_f32 v[60:61], v[60:61], v[152:153]
	v_pk_mul_f32 v[56:57], v[56:57], v[156:157]
	v_pk_mul_f32 v[52:53], v[52:53], v[218:219]
	v_pk_mul_f32 v[62:63], v[62:63], v[146:147]
	v_pk_mul_f32 v[58:59], v[58:59], v[150:151]
	v_pk_mul_f32 v[54:55], v[54:55], v[154:155]
	v_pk_mul_f32 v[50:51], v[50:51], v[216:217]
	v_pk_mul_f32 v[48:49], v[48:49], v[148:149]
	v_pk_mul_f32 v[44:45], v[44:45], v[152:153]
	v_pk_mul_f32 v[40:41], v[40:41], v[156:157]
	v_pk_mul_f32 v[36:37], v[36:37], v[218:219]
	v_pk_mul_f32 v[46:47], v[46:47], v[146:147]
	v_pk_mul_f32 v[42:43], v[42:43], v[150:151]
	v_pk_mul_f32 v[38:39], v[38:39], v[154:155]
	v_pk_mul_f32 v[34:35], v[34:35], v[216:217]
	v_pk_mul_f32 v[32:33], v[32:33], v[148:149]
	v_pk_mul_f32 v[28:29], v[28:29], v[152:153]
	v_pk_mul_f32 v[24:25], v[24:25], v[156:157]
	v_pk_mul_f32 v[20:21], v[20:21], v[218:219]
	v_pk_mul_f32 v[30:31], v[30:31], v[146:147]
	v_pk_mul_f32 v[26:27], v[26:27], v[150:151]
	v_pk_mul_f32 v[22:23], v[22:23], v[154:155]
	v_pk_mul_f32 v[18:19], v[18:19], v[216:217]
